# attention main loop: LDS-DMA destination set with one s_add_i32 m0 instead of add + move (5 scalar ops per iteration removed)
# baseline (speedup 1.0000x reference)
.LBB0_832:
	v_cvt_pk_bf16_f32 v172, v104, v105
	v_cvt_pk_bf16_f32 v180, v96, v97
	s_add_i32 s12, s67, -3
	s_and_b32 s22, s12, 3
	s_mulk_i32 s22, 0x3000
	v_add_u32_e32 v0, s22, v214
	ds_read_b128 v[2:5], v0 offset:4096
	v_add_u32_e32 v14, s101, v217
	s_waitcnt lgkmcnt(4)
	v_mfma_f32_32x32x16_bf16 v[128:143], v[196:199], v[176:179], v[64:79]
	v_add_f32_e32 v6, v96, v97
	v_add_f32_e32 v6, v98, v6
	v_add_f32_e32 v6, v99, v6
	v_add_f32_e32 v10, v100, v6
	ds_read_b128 v[6:9], v0 offset:4608
	s_waitcnt lgkmcnt(4)
	v_mfma_f32_32x32x16_bf16 v[112:127], v[184:187], v[176:179], v[64:79]
	v_add_f32_e32 v10, v101, v10
	v_add_f32_e32 v10, v102, v10
	v_add_f32_e32 v15, v103, v10
	v_cvt_pk_bf16_f32 v181, v98, v99
	s_add_u32 s62, s58, 0xffff0000
	s_addc_u32 s63, s59, -1
	s_and_b32 s12, s67, 3
	s_mulk_i32 s12, 0x3000
	s_add_i32 s64, s12, s78
	s_mov_b32 m0, s64
	s_nop 0
	global_load_lds_dwordx4 v216, s[62:63]
	ds_read_b128 v[10:13], v0 offset:6144
	s_waitcnt lgkmcnt(4)
	v_mfma_f32_32x32x16_bf16 v[128:143], v[188:191], v[168:171], v[128:143]
	v_add_f32_e32 v15, v104, v15
	v_add_f32_e32 v15, v105, v15
	v_add_f32_e32 v15, v106, v15
	v_cvt_pk_bf16_f32 v182, v100, v101
	ds_read_b128 v[96:99], v0 offset:6656
	s_waitcnt lgkmcnt(4)
	v_mfma_f32_32x32x16_bf16 v[112:127], v[192:195], v[168:171], v[112:127]
	v_add_f32_e32 v15, v107, v15
	v_add_f32_e32 v15, v108, v15
	v_add_f32_e32 v15, v109, v15
	v_cvt_pk_bf16_f32 v183, v102, v103
	s_add_u32 s62, s60, 0xfffff000
	s_addc_u32 s63, s61, -1
	s_add_i32 m0, s12, s85
	s_nop 0
	global_load_lds_dwordx4 v216, s[62:63]
	ds_read_b128 v[100:103], v0 offset:8192
	s_waitcnt lgkmcnt(4)
	v_mfma_f32_32x32x16_bf16 v[128:143], v[2:5], v[164:167], v[128:143]
	v_add_f32_e32 v15, v110, v15
	v_add_f32_e32 v15, v111, v15
	v_add_f32_e32 v15, v80, v15
	ds_read_b128 v[2:5], v0 offset:8704
	s_waitcnt lgkmcnt(4)
	v_mfma_f32_32x32x16_bf16 v[112:127], v[6:9], v[164:167], v[112:127]
	v_add_f32_e32 v15, v81, v15
	v_add_f32_e32 v15, v82, v15
	v_add_f32_e32 v15, v83, v15
	v_cvt_pk_bf16_f32 v173, v106, v107
	s_add_u32 s62, s6, 0xffff0000
	s_addc_u32 s63, s7, -1
	s_add_i32 m0, s23, s86
	s_nop 0
	global_load_lds_dwordx4 v216, s[62:63]
	ds_read_b128 v[104:107], v0 offset:10240
	s_waitcnt lgkmcnt(4)
	v_mfma_f32_32x32x16_bf16 v[128:143], v[10:13], v[156:159], v[128:143]
	v_add_f32_e32 v6, v84, v15
	v_add_f32_e32 v6, v85, v6
	v_cvt_pk_bf16_f32 v174, v108, v109
	v_cvt_pk_bf16_f32 v175, v110, v111
	ds_read_b128 v[108:111], v0 offset:10752
	s_waitcnt lgkmcnt(4)
	v_mfma_f32_32x32x16_bf16 v[112:127], v[96:99], v[156:159], v[112:127]
	v_add_f32_e32 v0, v86, v6
	v_add_f32_e32 v0, v87, v0
	v_cvt_pk_bf16_f32 v160, v80, v81
	v_cvt_pk_bf16_f32 v161, v82, v83
	ds_read_b64_tr_b16 v[6:7], v14 offset:49152
	ds_read_b64_tr_b16 v[8:9], v14 offset:49664
	s_waitcnt lgkmcnt(5)
	v_mfma_f32_32x32x16_bf16 v[128:143], v[100:103], v[148:151], v[128:143]
	v_add_f32_e32 v0, v88, v0
	v_add_f32_e32 v0, v89, v0
	v_cvt_pk_bf16_f32 v162, v84, v85
	v_cvt_pk_bf16_f32 v163, v86, v87
	ds_read_b64_tr_b16 v[10:11], v14 offset:53248
	ds_read_b64_tr_b16 v[12:13], v14 offset:53760
	s_waitcnt lgkmcnt(6)
	v_mfma_f32_32x32x16_bf16 v[112:127], v[2:5], v[148:151], v[112:127]
	v_add_f32_e32 v0, v90, v0
	v_add_f32_e32 v0, v91, v0
	v_cvt_pk_bf16_f32 v152, v88, v89
	v_cvt_pk_bf16_f32 v153, v90, v91
	ds_read_b64_tr_b16 v[80:81], v14 offset:50176
	ds_read_b64_tr_b16 v[82:83], v14 offset:50688
	s_waitcnt lgkmcnt(7)
	v_mfma_f32_32x32x16_bf16 v[128:143], v[104:107], v[144:147], v[128:143]
	v_add_f32_e32 v0, v92, v0
	v_add_f32_e32 v0, v93, v0
	v_cvt_pk_bf16_f32 v154, v92, v93
	ds_read_b64_tr_b16 v[2:3], v14 offset:54272
	ds_read_b64_tr_b16 v[4:5], v14 offset:54784
	s_waitcnt lgkmcnt(8)
	v_mfma_f32_32x32x16_bf16 v[112:127], v[108:111], v[144:147], v[112:127]
	v_add_f32_e32 v0, v94, v0
	v_add_f32_e32 v0, v95, v0
	v_cvt_pk_bf16_f32 v155, v94, v95
	s_nop 1
	v_max_f32_e32 v15, v128, v129
	s_add_i32 s12, s67, -2
	s_and_b32 s12, s12, 3
	s_mulk_i32 s12, 0x3000
	s_nop 2
	v_max3_f32 v84, v130, v131, v113
	v_max3_f32 v15, v15, v112, v114
	v_max3_f32 v15, v15, v115, v132
	v_max3_f32 v84, v84, v134, v135
	v_max3_f32 v15, v15, v133, v116
	v_max3_f32 v84, v84, v118, v119
	v_max3_f32 v15, v15, v117, v136
	v_max3_f32 v84, v84, v138, v139
	v_max3_f32 v15, v15, v137, v120
	v_max3_f32 v84, v84, v122, v123
	v_max3_f32 v15, v15, v121, v140
	v_max3_f32 v84, v84, v142, v143
	v_max3_f32 v15, v15, v141, v124
	v_max3_f32 v84, v84, v126, v127
	v_max3_f32 v15, v15, v125, v84
	v_mov_b32_e32 v84, v15
	s_nop 1
	v_permlane32_swap_b32_e32 v15, v84
	v_max_f32_e32 v15, v15, v84
	v_cmp_lt_f32_e32 vcc, s94, v15
	s_cmp_lg_u64 vcc, 0
	v_add_f32_e32 v0, v218, v0
	s_cselect_b64 s[62:63], -1, 0
	s_cbranch_vccnz .LBB0_840

.LBB0_835:
	ds_read_b128 v[188:191], v15 offset:4096
	v_add_u32_e32 v14, s10, v217
	s_waitcnt lgkmcnt(4)
	v_mfma_f32_32x32x16_bf16 v[96:111], v[2:5], v[176:179], v[64:79]
	v_add_f32_e32 v80, v128, v129
	v_add_f32_e32 v80, v130, v80
	v_add_f32_e32 v80, v131, v80
	v_add_f32_e32 v80, v132, v80
	v_cvt_pk_bf16_f32 v180, v128, v129
	ds_read_b128 v[2:5], v15 offset:4608
	v_add_f32_e32 v80, v133, v80
	v_add_f32_e32 v80, v134, v80
	v_add_f32_e32 v128, v135, v80
	s_waitcnt lgkmcnt(4)
	v_mfma_f32_32x32x16_bf16 v[80:95], v[6:9], v[176:179], v[64:79]
	v_cvt_pk_bf16_f32 v181, v130, v131
	s_add_i32 m0, s22, s78
	s_nop 0
	global_load_lds_dwordx4 v216, s[58:59]
	ds_read_b128 v[6:9], v15 offset:6144
	s_waitcnt lgkmcnt(4)
	v_mfma_f32_32x32x16_bf16 v[96:111], v[10:13], v[168:171], v[96:111]
	v_add_f32_e32 v128, v136, v128
	v_add_f32_e32 v128, v137, v128
	v_add_f32_e32 v128, v138, v128
	v_cvt_pk_bf16_f32 v182, v132, v133
	ds_read_b128 v[10:13], v15 offset:6656
	s_waitcnt lgkmcnt(4)
	v_mfma_f32_32x32x16_bf16 v[80:95], v[184:187], v[168:171], v[80:95]
	v_add_f32_e32 v128, v139, v128
	v_add_f32_e32 v128, v140, v128
	v_add_f32_e32 v132, v141, v128
	v_cvt_pk_bf16_f32 v183, v134, v135
	s_add_i32 m0, s22, s85
	s_nop 0
	global_load_lds_dwordx4 v216, s[60:61]
	ds_read_b128 v[128:131], v15 offset:8192
	s_waitcnt lgkmcnt(4)
	v_mfma_f32_32x32x16_bf16 v[96:111], v[188:191], v[164:167], v[96:111]
	v_add_f32_e32 v132, v142, v132
	v_add_f32_e32 v132, v143, v132
	v_add_f32_e32 v152, v112, v132
	v_cvt_pk_bf16_f32 v172, v136, v137
	ds_read_b128 v[132:135], v15 offset:8704
	s_waitcnt lgkmcnt(4)
	v_mfma_f32_32x32x16_bf16 v[80:95], v[2:5], v[164:167], v[80:95]
	v_add_f32_e32 v136, v113, v152
	v_add_f32_e32 v136, v114, v136
	v_add_f32_e32 v136, v115, v136
	v_cvt_pk_bf16_f32 v173, v138, v139
	s_add_i32 m0, s12, s86
	s_nop 0
	global_load_lds_dwordx4 v216, s[6:7]
	ds_read_b128 v[2:5], v15 offset:10240
	s_waitcnt lgkmcnt(4)
	v_mfma_f32_32x32x16_bf16 v[96:111], v[6:9], v[156:159], v[96:111]
	v_add_f32_e32 v136, v116, v136
	v_add_f32_e32 v152, v117, v136
	v_cvt_pk_bf16_f32 v174, v140, v141
	v_cvt_pk_bf16_f32 v175, v142, v143
	ds_read_b128 v[136:139], v15 offset:10752
	s_waitcnt lgkmcnt(4)
	v_mfma_f32_32x32x16_bf16 v[80:95], v[10:13], v[156:159], v[80:95]
	v_add_f32_e32 v6, v118, v152
	v_add_f32_e32 v6, v119, v6
	v_cvt_pk_bf16_f32 v160, v112, v113
	v_cvt_pk_bf16_f32 v161, v114, v115
	ds_read_b64_tr_b16 v[112:113], v14 offset:49152
	ds_read_b64_tr_b16 v[114:115], v14 offset:49664
	s_waitcnt lgkmcnt(5)
	v_mfma_f32_32x32x16_bf16 v[96:111], v[128:131], v[148:151], v[96:111]
	v_add_f32_e32 v6, v120, v6
	v_add_f32_e32 v6, v121, v6
	v_cvt_pk_bf16_f32 v162, v116, v117
	v_cvt_pk_bf16_f32 v163, v118, v119
	ds_read_b64_tr_b16 v[10:11], v14 offset:53248
	ds_read_b64_tr_b16 v[12:13], v14 offset:53760
	s_waitcnt lgkmcnt(6)
	v_mfma_f32_32x32x16_bf16 v[80:95], v[132:135], v[148:151], v[80:95]
	v_add_f32_e32 v6, v122, v6
	v_add_f32_e32 v15, v123, v6
	v_cvt_pk_bf16_f32 v152, v120, v121
	v_cvt_pk_bf16_f32 v153, v122, v123
	ds_read_b64_tr_b16 v[6:7], v14 offset:50176
	ds_read_b64_tr_b16 v[8:9], v14 offset:50688
	s_waitcnt lgkmcnt(7)
	v_mfma_f32_32x32x16_bf16 v[96:111], v[2:5], v[144:147], v[96:111]
	v_add_f32_e32 v15, v124, v15
	v_add_f32_e32 v15, v125, v15
	v_cvt_pk_bf16_f32 v154, v124, v125
	ds_read_b64_tr_b16 v[2:3], v14 offset:54272
	ds_read_b64_tr_b16 v[4:5], v14 offset:54784
	s_waitcnt lgkmcnt(8)
	v_mfma_f32_32x32x16_bf16 v[80:95], v[136:139], v[144:147], v[80:95]
	v_add_f32_e32 v15, v126, v15
	v_add_f32_e32 v15, v127, v15
	v_cvt_pk_bf16_f32 v155, v126, v127
	s_nop 1
	v_max_f32_e32 v116, v96, v97
	s_add_i32 s10, s67, -1
	s_and_b32 s22, s10, 3
	s_mulk_i32 s22, 0x3000
	s_nop 2
	v_max3_f32 v117, v98, v99, v81
	v_max3_f32 v116, v116, v80, v82
	v_max3_f32 v116, v116, v83, v100
	v_max3_f32 v117, v117, v102, v103
	v_max3_f32 v116, v116, v101, v84
	v_max3_f32 v117, v117, v86, v87
	v_max3_f32 v116, v116, v85, v104
	v_max3_f32 v117, v117, v106, v107
	v_max3_f32 v116, v116, v105, v88
	v_max3_f32 v117, v117, v90, v91
	v_max3_f32 v116, v116, v89, v108
	v_max3_f32 v117, v117, v110, v111
	v_max3_f32 v116, v116, v109, v92
	v_max3_f32 v117, v117, v94, v95
	v_add_f32_e32 v218, v0, v15
	v_max3_f32 v0, v116, v93, v117
	v_mov_b32_e32 v15, v0
	s_nop 1
	v_permlane32_swap_b32_e32 v0, v15
	v_max_f32_e32 v0, v0, v15
	v_cmp_lt_f32_e32 vcc, s94, v0
	s_cmp_lg_u64 vcc, 0
	s_cselect_b64 s[62:63], -1, 0
	s_cbranch_vccnz .LBB0_843
